# v17: v4 plus next-step cache-touch loads in the sample-attention P.V loop so its 16 value-row loads per step no longer expose HBM latency
# baseline (speedup 1.0000x reference)
.LBB0_1342:
	v_add_co_u32_e32 v12, vcc, s52, v8
	global_load_dword v10, v[8:9], off
	s_nop 0
	v_addc_co_u32_e32 v13, vcc, 0, v9, vcc
	v_add_co_u32_e32 v14, vcc, s61, v8
	v_mov_b32_e32 v11, s1
	s_nop 0
	v_addc_co_u32_e32 v15, vcc, 0, v9, vcc
	v_add_co_u32_e32 v174, vcc, s66, v8
	ds_read_b128 v[16:19], v11
	ds_read_b128 v[20:23], v11 offset:16
	ds_read_b128 v[24:27], v11 offset:32
	ds_read_b128 v[28:31], v11 offset:48
	ds_read_b128 v[32:35], v11 offset:4176
	ds_read_b128 v[36:39], v11 offset:4192
	ds_read_b128 v[40:43], v11 offset:4208
	ds_read_b128 v[44:47], v11 offset:4224
	ds_read_b128 v[48:51], v11 offset:8352
	ds_read_b128 v[52:55], v11 offset:8368
	ds_read_b128 v[56:59], v11 offset:8384
	ds_read_b128 v[60:63], v11 offset:8400
	ds_read_b128 v[88:91], v11 offset:12528
	ds_read_b128 v[102:105], v11 offset:12544
	ds_read_b128 v[106:109], v11 offset:12560
	ds_read_b128 v[110:113], v11 offset:12576
	ds_read_b128 v[114:117], v11 offset:16704
	ds_read_b128 v[118:121], v11 offset:16720
	ds_read_b128 v[122:125], v11 offset:16736
	ds_read_b128 v[126:129], v11 offset:16752
	ds_read_b128 v[130:133], v11 offset:20880
	ds_read_b128 v[134:137], v11 offset:20896
	ds_read_b128 v[138:141], v11 offset:20912
	ds_read_b128 v[142:145], v11 offset:20928
	ds_read_b128 v[146:149], v11 offset:25056
	ds_read_b128 v[150:153], v11 offset:25072
	ds_read_b128 v[154:157], v11 offset:25088
	ds_read_b128 v[158:161], v11 offset:25104
	ds_read_b128 v[162:165], v11 offset:29232
	ds_read_b128 v[166:169], v11 offset:29248
	ds_read_b128 v[170:173], v11 offset:29264
	ds_read_b128 v[182:185], v11 offset:29280
	v_addc_co_u32_e32 v175, vcc, 0, v9, vcc
	v_add_co_u32_e32 v188, vcc, s67, v8
	global_load_dword v66, v[12:13], off offset:-4096
	s_nop 0
	global_load_dword v12, v[12:13], off
	s_nop 0
	global_load_dword v186, v[14:15], off offset:-4096
	s_nop 0
	global_load_dword v14, v[14:15], off
	v_addc_co_u32_e32 v189, vcc, 0, v9, vcc
	v_add_co_u32_e32 v190, vcc, s68, v8
	global_load_dword v192, v[174:175], off offset:-4096
	s_nop 0
	global_load_dword v174, v[174:175], off
	s_nop 0
	global_load_dword v194, v[188:189], off offset:-4096
	s_nop 0
	global_load_dword v188, v[188:189], off
	v_addc_co_u32_e32 v191, vcc, 0, v9, vcc
	v_add_co_u32_e32 v196, vcc, s69, v8
	s_waitcnt lgkmcnt(14)
	v_mov_b32_e32 v206, v32
	v_addc_co_u32_e32 v197, vcc, 0, v9, vcc
	v_add_co_u32_e32 v198, vcc, s70, v8
	global_load_dword v200, v[190:191], off offset:-4096
	s_nop 0
	global_load_dword v190, v[190:191], off
	s_nop 0
	global_load_dword v202, v[196:197], off offset:-4096
	v_addc_co_u32_e32 v199, vcc, 0, v9, vcc
	v_add_co_u32_e32 v204, vcc, s71, v8
	v_mov_b32_e32 v32, v34
	s_nop 0
	v_addc_co_u32_e32 v205, vcc, 0, v9, vcc
	v_mov_b32_e32 v34, v36
	v_mov_b32_e32 v36, v38
	v_mov_b32_e32 v38, v40
	v_mov_b32_e32 v40, v42
	v_mov_b32_e32 v42, v44
	v_mov_b32_e32 v44, v46
	v_mov_b32_e32 v46, v88
	v_mov_b32_e32 v88, v90
	v_mov_b32_e32 v90, v102
	v_mov_b32_e32 v102, v104
	v_mov_b32_e32 v104, v106
	v_mov_b32_e32 v106, v108
	v_mov_b32_e32 v108, v110
	v_mov_b32_e32 v110, v112
	s_waitcnt lgkmcnt(11)
	v_mov_b32_e32 v112, v130
	v_mov_b32_e32 v130, v132
	s_waitcnt lgkmcnt(10)
	v_mov_b32_e32 v132, v134
	v_mov_b32_e32 v134, v136
	s_waitcnt lgkmcnt(9)
	v_mov_b32_e32 v136, v138
	v_mov_b32_e32 v138, v140
	s_waitcnt lgkmcnt(8)
	v_mov_b32_e32 v140, v142
	v_mov_b32_e32 v142, v144
	s_waitcnt lgkmcnt(3)
	v_mov_b32_e32 v144, v162
	v_mov_b32_e32 v162, v164
	s_waitcnt lgkmcnt(2)
	v_mov_b32_e32 v164, v166
	v_mov_b32_e32 v166, v168
	s_waitcnt lgkmcnt(1)
	v_mov_b32_e32 v168, v170
	v_mov_b32_e32 v170, v172
	s_waitcnt lgkmcnt(0)
	v_mov_b32_e32 v172, v182
	v_mov_b32_e32 v182, v184
	global_load_dword v184, v[196:197], off
	s_nop 0
	global_load_dword v196, v[198:199], off offset:-4096
	s_nop 0
	global_load_dword v198, v[198:199], off
	v_mov_b32_e32 v207, v16
	global_load_dword v204, v[204:205], off
	s_add_i32 s98, s0, 16
	s_cmp_ge_i32 s98, s81
	s_cselect_b32 s98, 0, 0x10000
	s_mov_b32 s99, 0
	s_mov_b64 s[100:101], 0x2000
	v_lshl_add_u64 v[224:225], v[8:9], 0, s[98:99]
	global_load_dword v253, v[224:225], off
	v_lshl_add_u64 v[226:227], v[224:225], 0, s[100:101]
	global_load_dword v253, v[226:227], off offset:-4096
	global_load_dword v253, v[226:227], off
	v_lshl_add_u64 v[228:229], v[226:227], 0, s[100:101]
	global_load_dword v253, v[228:229], off offset:-4096
	global_load_dword v253, v[228:229], off
	v_lshl_add_u64 v[230:231], v[228:229], 0, s[100:101]
	global_load_dword v253, v[230:231], off offset:-4096
	global_load_dword v253, v[230:231], off
	v_lshl_add_u64 v[232:233], v[230:231], 0, s[100:101]
	global_load_dword v253, v[232:233], off offset:-4096
	global_load_dword v253, v[232:233], off
	v_lshl_add_u64 v[234:235], v[232:233], 0, s[100:101]
	global_load_dword v253, v[234:235], off offset:-4096
	global_load_dword v253, v[234:235], off
	v_lshl_add_u64 v[236:237], v[234:235], 0, s[100:101]
	global_load_dword v253, v[236:237], off offset:-4096
	global_load_dword v253, v[236:237], off
	v_lshl_add_u64 v[238:239], v[236:237], 0, s[100:101]
	global_load_dword v253, v[238:239], off offset:-4096
	global_load_dword v253, v[238:239], off
	v_lshl_add_u64 v[240:241], v[238:239], 0, s[100:101]
	global_load_dword v253, v[240:241], off offset:-4096
	v_mov_b32_e32 v16, v33
	v_mov_b32_e32 v33, v18
	v_mov_b32_e32 v18, v35
	v_mov_b32_e32 v35, v20
	v_mov_b32_e32 v20, v37
	v_mov_b32_e32 v37, v22
	v_mov_b32_e32 v22, v39
	v_mov_b32_e32 v39, v24
	v_mov_b32_e32 v24, v41
	v_mov_b32_e32 v41, v26
	v_mov_b32_e32 v26, v43
	v_mov_b32_e32 v43, v28
	v_mov_b32_e32 v28, v45
	v_mov_b32_e32 v45, v30
	v_mov_b32_e32 v30, v47
	v_mov_b32_e32 v47, v48
	v_mov_b32_e32 v48, v89
	v_mov_b32_e32 v89, v50
	v_mov_b32_e32 v50, v91
	v_mov_b32_e32 v91, v52
	v_mov_b32_e32 v52, v103
	v_mov_b32_e32 v103, v54
	v_mov_b32_e32 v54, v105
	v_mov_b32_e32 v105, v56
	v_mov_b32_e32 v56, v107
	v_mov_b32_e32 v107, v58
	v_mov_b32_e32 v58, v109
	v_mov_b32_e32 v109, v60
	v_mov_b32_e32 v60, v111
	v_mov_b32_e32 v111, v62
	v_mov_b32_e32 v62, v113
	v_mov_b32_e32 v113, v114
	v_mov_b32_e32 v114, v131
	v_mov_b32_e32 v131, v116
	v_mov_b32_e32 v116, v133
	v_mov_b32_e32 v133, v118
	v_mov_b32_e32 v118, v135
	v_mov_b32_e32 v135, v120
	v_mov_b32_e32 v120, v137
	v_mov_b32_e32 v137, v122
	v_mov_b32_e32 v122, v139
	v_mov_b32_e32 v139, v124
	v_mov_b32_e32 v124, v141
	v_mov_b32_e32 v141, v126
	v_mov_b32_e32 v126, v143
	v_mov_b32_e32 v143, v128
	v_mov_b32_e32 v128, v145
	v_mov_b32_e32 v145, v146
	v_mov_b32_e32 v146, v163
	v_mov_b32_e32 v163, v148
	v_mov_b32_e32 v148, v165
	s_waitcnt vmcnt(30)
	v_pk_mul_f32 v[48:49], v[66:67], v[48:49] op_sel_hi:[0,1]
	v_pk_mul_f32 v[114:115], v[66:67], v[114:115] op_sel_hi:[0,1]
	v_mov_b32_e32 v165, v150
	v_mov_b32_e32 v150, v167
	v_pk_mul_f32 v[16:17], v[66:67], v[16:17] op_sel_hi:[0,1]
	v_pk_mul_f32 v[146:147], v[66:67], v[146:147] op_sel_hi:[0,1]
	s_waitcnt vmcnt(28)
	v_pk_mul_f32 v[18:19], v[186:187], v[18:19] op_sel_hi:[0,1]
	v_pk_fma_f32 v[46:47], v[10:11], v[46:47], v[48:49] op_sel_hi:[0,1,1]
	v_pk_mul_f32 v[48:49], v[186:187], v[50:51] op_sel_hi:[0,1]
	v_pk_fma_f32 v[50:51], v[10:11], v[112:113], v[114:115] op_sel_hi:[0,1,1]
	v_pk_mul_f32 v[112:113], v[186:187], v[116:117] op_sel_hi:[0,1]
	v_pk_mul_f32 v[114:115], v[186:187], v[148:149] op_sel_hi:[0,1]
	v_mov_b32_e32 v167, v152
	v_mov_b32_e32 v152, v169
	v_pk_fma_f32 v[16:17], v[10:11], v[206:207], v[16:17] op_sel_hi:[0,1,1]
	v_pk_fma_f32 v[10:11], v[10:11], v[144:145], v[146:147] op_sel_hi:[0,1,1]
	v_pk_fma_f32 v[18:19], v[12:13], v[32:33], v[18:19] op_sel_hi:[0,1,1]
	s_waitcnt vmcnt(26)
	v_pk_mul_f32 v[20:21], v[192:193], v[20:21] op_sel_hi:[0,1]
	v_pk_fma_f32 v[32:33], v[12:13], v[88:89], v[48:49] op_sel_hi:[0,1,1]
	v_pk_mul_f32 v[48:49], v[192:193], v[52:53] op_sel_hi:[0,1]
	v_pk_fma_f32 v[52:53], v[12:13], v[130:131], v[112:113] op_sel_hi:[0,1,1]
	v_pk_mul_f32 v[88:89], v[192:193], v[118:119] op_sel_hi:[0,1]
	v_pk_fma_f32 v[12:13], v[12:13], v[162:163], v[114:115] op_sel_hi:[0,1,1]
	v_pk_mul_f32 v[112:113], v[192:193], v[150:151] op_sel_hi:[0,1]
	v_mov_b32_e32 v169, v154
	v_mov_b32_e32 v154, v171
	v_pk_add_f32 v[16:17], v[16:17], v[18:19]
	v_pk_fma_f32 v[18:19], v[14:15], v[34:35], v[20:21] op_sel_hi:[0,1,1]
	s_waitcnt vmcnt(24)
	v_pk_mul_f32 v[20:21], v[194:195], v[22:23] op_sel_hi:[0,1]
	v_pk_add_f32 v[22:23], v[46:47], v[32:33]
	v_pk_fma_f32 v[32:33], v[14:15], v[90:91], v[48:49] op_sel_hi:[0,1,1]
	v_pk_mul_f32 v[34:35], v[194:195], v[54:55] op_sel_hi:[0,1]
	v_pk_add_f32 v[46:47], v[50:51], v[52:53]
	v_pk_fma_f32 v[48:49], v[14:15], v[132:133], v[88:89] op_sel_hi:[0,1,1]
	v_pk_mul_f32 v[50:51], v[194:195], v[120:121] op_sel_hi:[0,1]
	v_pk_add_f32 v[10:11], v[10:11], v[12:13]
	v_pk_fma_f32 v[12:13], v[14:15], v[164:165], v[112:113] op_sel_hi:[0,1,1]
	v_pk_mul_f32 v[14:15], v[194:195], v[152:153] op_sel_hi:[0,1]
	v_mov_b32_e32 v171, v156
	v_mov_b32_e32 v156, v173
	v_pk_add_f32 v[6:7], v[6:7], v[16:17]
	v_pk_fma_f32 v[16:17], v[174:175], v[36:37], v[20:21] op_sel_hi:[0,1,1]
	s_waitcnt vmcnt(22)
	v_pk_mul_f32 v[20:21], v[200:201], v[24:25] op_sel_hi:[0,1]
	v_pk_add_f32 v[4:5], v[4:5], v[22:23]
	v_pk_fma_f32 v[22:23], v[174:175], v[102:103], v[34:35] op_sel_hi:[0,1,1]
	v_pk_fma_f32 v[34:35], v[174:175], v[134:135], v[50:51] op_sel_hi:[0,1,1]
	v_pk_add_f32 v[0:1], v[0:1], v[10:11]
	v_pk_fma_f32 v[10:11], v[174:175], v[166:167], v[14:15] op_sel_hi:[0,1,1]
	v_pk_mul_f32 v[14:15], v[200:201], v[154:155] op_sel_hi:[0,1]
	v_mov_b32_e32 v173, v158
	v_mov_b32_e32 v158, v183
	v_pk_mul_f32 v[24:25], v[200:201], v[56:57] op_sel_hi:[0,1]
	v_pk_add_f32 v[2:3], v[2:3], v[46:47]
	v_pk_mul_f32 v[36:37], v[200:201], v[122:123] op_sel_hi:[0,1]
	v_pk_add_f32 v[16:17], v[18:19], v[16:17]
	v_pk_fma_f32 v[18:19], v[188:189], v[38:39], v[20:21] op_sel_hi:[0,1,1]
	s_waitcnt vmcnt(20)
	v_pk_mul_f32 v[20:21], v[202:203], v[26:27] op_sel_hi:[0,1]
	v_pk_add_f32 v[22:23], v[32:33], v[22:23]
	v_pk_mul_f32 v[26:27], v[202:203], v[58:59] op_sel_hi:[0,1]
	v_pk_add_f32 v[32:33], v[48:49], v[34:35]
	v_pk_add_f32 v[10:11], v[12:13], v[10:11]
	v_pk_fma_f32 v[12:13], v[188:189], v[168:169], v[14:15] op_sel_hi:[0,1,1]
	v_pk_mul_f32 v[14:15], v[202:203], v[156:157] op_sel_hi:[0,1]
	v_mov_b32_e32 v183, v160
	v_mov_b32_e32 v160, v185
	v_pk_fma_f32 v[24:25], v[188:189], v[104:105], v[24:25] op_sel_hi:[0,1,1]
	v_pk_fma_f32 v[34:35], v[188:189], v[136:137], v[36:37] op_sel_hi:[0,1,1]
	v_pk_mul_f32 v[36:37], v[202:203], v[124:125] op_sel_hi:[0,1]
	v_pk_add_f32 v[6:7], v[6:7], v[16:17]
	v_pk_fma_f32 v[16:17], v[190:191], v[40:41], v[20:21] op_sel_hi:[0,1,1]
	s_waitcnt vmcnt(18)
	v_pk_mul_f32 v[20:21], v[196:197], v[28:29] op_sel_hi:[0,1]
	v_pk_add_f32 v[4:5], v[4:5], v[22:23]
	v_pk_fma_f32 v[22:23], v[190:191], v[106:107], v[26:27] op_sel_hi:[0,1,1]
	v_pk_mul_f32 v[26:27], v[196:197], v[60:61] op_sel_hi:[0,1]
	v_pk_add_f32 v[2:3], v[2:3], v[32:33]
	v_pk_mul_f32 v[32:33], v[196:197], v[126:127] op_sel_hi:[0,1]
	v_pk_add_f32 v[0:1], v[0:1], v[10:11]
	v_pk_fma_f32 v[10:11], v[190:191], v[170:171], v[14:15] op_sel_hi:[0,1,1]
	v_pk_mul_f32 v[14:15], v[196:197], v[158:159] op_sel_hi:[0,1]
	v_pk_fma_f32 v[28:29], v[190:191], v[138:139], v[36:37] op_sel_hi:[0,1,1]
	v_pk_add_f32 v[16:17], v[18:19], v[16:17]
	v_pk_fma_f32 v[18:19], v[184:185], v[42:43], v[20:21] op_sel_hi:[0,1,1]
	s_waitcnt vmcnt(16)
	v_pk_mul_f32 v[20:21], v[204:205], v[30:31] op_sel_hi:[0,1]
	v_pk_add_f32 v[22:23], v[24:25], v[22:23]
	v_pk_fma_f32 v[24:25], v[184:185], v[108:109], v[26:27] op_sel_hi:[0,1,1]
	v_pk_mul_f32 v[26:27], v[204:205], v[62:63] op_sel_hi:[0,1]
	v_pk_fma_f32 v[30:31], v[184:185], v[140:141], v[32:33] op_sel_hi:[0,1,1]
	v_pk_mul_f32 v[32:33], v[204:205], v[128:129] op_sel_hi:[0,1]
	v_pk_add_f32 v[10:11], v[12:13], v[10:11]
	v_pk_fma_f32 v[12:13], v[184:185], v[172:173], v[14:15] op_sel_hi:[0,1,1]
	v_pk_mul_f32 v[14:15], v[204:205], v[160:161] op_sel_hi:[0,1]
	v_pk_add_f32 v[28:29], v[34:35], v[28:29]
	v_pk_add_f32 v[6:7], v[6:7], v[16:17]
	v_pk_fma_f32 v[16:17], v[198:199], v[44:45], v[20:21] op_sel_hi:[0,1,1]
	v_pk_add_f32 v[4:5], v[4:5], v[22:23]
	v_pk_fma_f32 v[20:21], v[198:199], v[110:111], v[26:27] op_sel_hi:[0,1,1]
	v_pk_fma_f32 v[22:23], v[198:199], v[142:143], v[32:33] op_sel_hi:[0,1,1]
	v_pk_add_f32 v[0:1], v[0:1], v[10:11]
	v_pk_fma_f32 v[10:11], v[198:199], v[182:183], v[14:15] op_sel_hi:[0,1,1]
	s_add_i32 s1, s1, 64
	s_add_i32 s0, s0, 16
	v_pk_add_f32 v[2:3], v[2:3], v[28:29]
	v_pk_add_f32 v[14:15], v[18:19], v[16:17]
	v_pk_add_f32 v[16:17], v[24:25], v[20:21]
	v_pk_add_f32 v[18:19], v[30:31], v[22:23]
	v_pk_add_f32 v[10:11], v[12:13], v[10:11]
	s_cmp_ge_i32 s0, s81
	v_lshl_add_u64 v[8:9], v[8:9], 0, s[22:23]
	v_pk_add_f32 v[6:7], v[6:7], v[14:15]
	v_pk_add_f32 v[4:5], v[4:5], v[16:17]
	v_pk_add_f32 v[2:3], v[2:3], v[18:19]
	v_pk_add_f32 v[0:1], v[0:1], v[10:11]
	s_cbranch_scc0 .LBB0_1342
	global_load_ushort v40, v[76:77], off
	global_load_ushort v41, v[78:79], off
	global_load_ushort v42, v[80:81], off
	global_load_ushort v43, v[82:83], off
	v_mov_b32_e32 v36, s80
	ds_read_b128 v[8:11], v36 offset:16464
	ds_read_b128 v[12:15], v36 offset:20640
	ds_read_b128 v[16:19], v36 offset:24816
	ds_read_b128 v[20:23], v36 offset:28992
	ds_read_b128 v[24:27], v36 offset:33168
	ds_read_b128 v[28:31], v36 offset:37344
	ds_read_b128 v[32:35], v36 offset:12288
	ds_read_b128 v[36:39], v36 offset:41520
	v_add_u32_e32 v44, 0x80, v95
	v_add_u32_e32 v45, 0x80, v96
	s_mov_b64 s[0:1], -1
	s_and_b64 vcc, exec, s[28:29]
	s_waitcnt vmcnt(3)
	v_lshlrev_b32_e32 v40, 16, v40
	s_waitcnt vmcnt(2)
	v_lshlrev_b32_e32 v41, 16, v41
	s_waitcnt vmcnt(1)
	v_lshlrev_b32_e32 v42, 16, v42
	s_waitcnt vmcnt(0)
	v_lshlrev_b32_e32 v43, 16, v43
	s_waitcnt lgkmcnt(1)
	v_mul_f32_e32 v33, v33, v41
	v_mul_f32_e32 v35, v35, v43
	v_mul_f32_e32 v9, v9, v41
	v_mul_f32_e32 v11, v11, v43
	v_mul_f32_e32 v13, v13, v41
	v_mul_f32_e32 v15, v15, v43
	v_mul_f32_e32 v17, v17, v41
	v_mul_f32_e32 v19, v19, v43
	v_mul_f32_e32 v21, v21, v41
	v_mul_f32_e32 v23, v23, v43
	v_mul_f32_e32 v25, v25, v41
	v_mul_f32_e32 v27, v27, v43
	v_mul_f32_e32 v29, v29, v41
	v_mul_f32_e32 v31, v31, v43
	s_waitcnt lgkmcnt(0)
	v_mul_f32_e32 v37, v37, v41
	v_mul_f32_e32 v39, v39, v43
	v_fmac_f32_e32 v33, v32, v40
	v_fmac_f32_e32 v35, v34, v42
	v_fmac_f32_e32 v9, v8, v40
	v_fmac_f32_e32 v11, v10, v42
	v_fmac_f32_e32 v13, v12, v40
	v_fmac_f32_e32 v15, v14, v42
	v_fmac_f32_e32 v17, v16, v40
	v_fmac_f32_e32 v19, v18, v42
	v_fmac_f32_e32 v21, v20, v40
	v_fmac_f32_e32 v23, v22, v42
	v_fmac_f32_e32 v25, v24, v40
	v_fmac_f32_e32 v27, v26, v42
	v_fmac_f32_e32 v29, v28, v40
	v_fmac_f32_e32 v31, v30, v42
	v_fmac_f32_e32 v37, v36, v40
	v_fmac_f32_e32 v39, v38, v42
	v_add_f32_e32 v8, v33, v35
	v_add_f32_e32 v9, v9, v11
	v_add_f32_e32 v10, v13, v15
	v_add_f32_e32 v11, v17, v19
	v_add_f32_e32 v12, v21, v23
	v_add_f32_e32 v13, v25, v27
	v_add_f32_e32 v14, v29, v31
	v_add_f32_e32 v15, v37, v39
	v_add_f32_e32 v7, v7, v8
	v_add_f32_e32 v6, v6, v9
	v_add_f32_e32 v5, v5, v10
	v_add_f32_e32 v4, v4, v11
	v_add_f32_e32 v3, v3, v12
	v_add_f32_e32 v2, v2, v13
	v_add_f32_e32 v1, v1, v14
	v_add_f32_e32 v0, v0, v15
	ds_write2st64_b32 v44, v7, v6 offset0:162 offset1:164
	ds_write2st64_b32 v44, v5, v4 offset0:166 offset1:168
	ds_write2st64_b32 v44, v3, v2 offset0:170 offset1:172
	ds_write2st64_b32 v44, v1, v0 offset0:174 offset1:176
	s_waitcnt lgkmcnt(0)
	s_barrier
	ds_read2st64_b64 v[0:3], v45 offset0:81 offset1:89
	ds_read2st64_b64 v[4:7], v45 offset0:97 offset1:105
	s_waitcnt lgkmcnt(1)
	v_pk_add_f32 v[0:1], v[0:1], v[2:3]
	s_waitcnt lgkmcnt(0)
	v_pk_add_f32 v[2:3], v[4:5], v[6:7]
	s_nop 0
	v_pk_add_f32 v[0:1], v[0:1], v[2:3]
	s_cbranch_vccz .LBB0_1345
	global_load_dwordx2 v[2:3], v[72:73], off
	ds_read_b64 v[4:5], v101 offset:57984
	s_mov_b64 s[0:1], 0
	s_waitcnt lgkmcnt(0)
	v_pk_fma_f32 v[4:5], v[64:65], v[0:1], v[4:5] neg_lo:[1,0,0] neg_hi:[1,0,0]
	s_nop 0
	v_pk_mul_f32 v[6:7], v[4:5], v[4:5]
	s_nop 0
	v_add_f32_e32 v6, v6, v7
	ds_bpermute_b32 v7, v176, v6
	s_waitcnt lgkmcnt(0)
	v_add_f32_e32 v6, v6, v7
	ds_bpermute_b32 v7, v177, v6
	s_waitcnt lgkmcnt(0)
	v_add_f32_e32 v6, v6, v7
	ds_bpermute_b32 v7, v178, v6
	s_waitcnt lgkmcnt(0)
	v_add_f32_e32 v6, v6, v7
	ds_bpermute_b32 v7, v179, v6
	s_waitcnt lgkmcnt(0)
	v_add_f32_e32 v6, v6, v7
	ds_bpermute_b32 v7, v180, v6
	s_waitcnt lgkmcnt(0)
	v_add_f32_e32 v6, v6, v7
	ds_bpermute_b32 v7, v181, v6
	s_waitcnt lgkmcnt(0)
	v_add_f32_e32 v6, v6, v7
	v_fmamk_f32 v6, v6, 0x3c000000, v92
	v_mul_f32_e32 v7, 0x4b800000, v6
	v_cmp_gt_f32_e32 vcc, s77, v6
	s_nop 1
	v_cndmask_b32_e32 v6, v6, v7, vcc
	v_rsq_f32_e32 v6, v6
	s_nop 0
	v_mul_f32_e32 v7, 0x45800000, v6
	v_cndmask_b32_e32 v6, v6, v7, vcc
	v_mul_f32_e32 v6, 0x3f24fd5c, v6
	v_pk_mul_f32 v[4:5], v[4:5], v[6:7] op_sel_hi:[1,0]
	s_waitcnt vmcnt(0)
	v_pk_mul_f32 v[2:3], v[2:3], v[4:5]
	s_nop 0
	v_cvt_pk_bf16_f32 v2, v2, v3
	global_store_dword v[74:75], v2, off
